# adds a code read-ahead in the last MLA unit's tail (covers the unit epilogue and the following grid barrier)
# baseline (speedup 1.0000x reference)
.Lmla_loop:
	v_exp_f32_e32 v34, v34
	v_exp_f32_e32 v35, v35
	v_exp_f32_e32 v36, v36
	s_waitcnt lgkmcnt(4)
	v_mfma_f32_32x32x16_bf16 v[66:81], v[138:141], v[98:101], v[122:137]
	ds_read_b128 v[138:141], v220 offset:13408
	v_exp_f32_e32 v37, v37
	v_add_f32_e32 v231, v231, v34
	v_add_f32_e32 v232, v232, v35
	v_exp_f32_e32 v38, v38
	v_mfma_f32_32x32x16_bf16 v[82:97], v[142:145], v[98:101], v[122:137]
	ds_read_b128 v[142:145], v220 offset:20064
	v_exp_f32_e32 v39, v39
	v_add_f32_e32 v231, v231, v36
	v_add_f32_e32 v232, v232, v37
	s_waitcnt lgkmcnt(4)
	v_mfma_f32_32x32x16_bf16 v[66:81], v[146:149], v[102:105], v[66:81]
	ds_read_b128 v[146:149], v220 offset:13440
	global_load_dwordx4 v[200:203], v226, s[4:5]
	global_load_dwordx4 v[204:207], v227, s[4:5]
	global_load_dwordx4 v[208:211], v228, s[4:5]
	s_add_u32 s4, s4, 0x6000
	s_addc_u32 s5, s5, 0
	global_load_dwordx4 v[212:215], v229, s[10:11]
	s_add_u32 s10, s10, 0x80
	s_addc_u32 s11, s11, 0
	v_exp_f32_e32 v40, v40
	v_exp_f32_e32 v41, v41
	v_add_f32_e32 v231, v231, v38
	v_add_f32_e32 v232, v232, v39
	v_mfma_f32_32x32x16_bf16 v[82:97], v[150:153], v[102:105], v[82:97]
	ds_read_b128 v[150:153], v220 offset:20096
	v_add_f32_e32 v231, v231, v40
	v_add_f32_e32 v232, v232, v41
	v_cvt_pk_bf16_f32 v34, v34, v35
	v_cvt_pk_bf16_f32 v35, v36, v37
	v_cvt_pk_bf16_f32 v36, v38, v39
	s_waitcnt lgkmcnt(4)
	v_mfma_f32_32x32x16_bf16 v[66:81], v[154:157], v[106:109], v[66:81]
	ds_read_b128 v[154:157], v220 offset:13472
	v_cvt_pk_bf16_f32 v37, v40, v41
	v_exp_f32_e32 v42, v42
	v_exp_f32_e32 v43, v43
	v_mfma_f32_32x32x16_bf16 v[82:97], v[158:161], v[106:109], v[82:97]
	ds_read_b128 v[158:161], v220 offset:20128
	v_exp_f32_e32 v44, v44
	v_exp_f32_e32 v45, v45
	v_add_f32_e32 v231, v231, v42
	v_add_f32_e32 v232, v232, v43
	s_waitcnt lgkmcnt(4)
	v_mfma_f32_32x32x16_bf16 v[66:81], v[138:141], v[110:113], v[66:81]
	ds_read_b128 v[162:165], v221 offset:0
	v_exp_f32_e32 v46, v46
	v_exp_f32_e32 v47, v47
	v_add_f32_e32 v231, v231, v44
	v_mfma_f32_32x32x16_bf16 v[82:97], v[142:145], v[110:113], v[82:97]
	ds_read_b128 v[166:169], v221 offset:4608
	v_add_f32_e32 v232, v232, v45
	v_exp_f32_e32 v48, v48
	v_exp_f32_e32 v49, v49
	s_waitcnt lgkmcnt(4)
	v_mfma_f32_32x32x16_bf16 v[66:81], v[146:149], v[114:117], v[66:81]
	ds_read_b128 v[170:173], v221 offset:32
	v_add_f32_e32 v231, v231, v46
	v_add_f32_e32 v232, v232, v47
	v_add_f32_e32 v231, v231, v48
	v_add_f32_e32 v232, v232, v49
	v_cvt_pk_bf16_f32 v42, v42, v43
	v_cvt_pk_bf16_f32 v43, v44, v45
	v_mfma_f32_32x32x16_bf16 v[82:97], v[150:153], v[114:117], v[82:97]
	ds_read_b128 v[174:177], v221 offset:4640
	v_cvt_pk_bf16_f32 v44, v46, v47
	v_cvt_pk_bf16_f32 v45, v48, v49
	v_exp_f32_e32 v50, v50
	v_exp_f32_e32 v51, v51
	s_waitcnt lgkmcnt(4)
	v_mfma_f32_32x32x16_bf16 v[66:81], v[154:157], v[118:121], v[66:81]
	ds_read_b128 v[180:183], v221 offset:64
	v_exp_f32_e32 v52, v52
	v_exp_f32_e32 v53, v53
	v_mfma_f32_32x32x16_bf16 v[82:97], v[158:161], v[118:121], v[82:97]
	ds_read_b128 v[184:187], v221 offset:4672
	v_add_f32_e32 v231, v231, v50
	v_add_f32_e32 v232, v232, v51
	v_exp_f32_e32 v54, v54
	v_exp_f32_e32 v55, v55
	s_waitcnt lgkmcnt(4)
	v_mfma_f32_32x32x16_bf16 v[2:17], v[162:165], v[34:37], v[2:17]
	ds_read_b128 v[188:191], v221 offset:96
	v_add_f32_e32 v231, v231, v52
	v_add_f32_e32 v232, v232, v53
	v_exp_f32_e32 v56, v56
	v_exp_f32_e32 v57, v57
	v_mfma_f32_32x32x16_bf16 v[18:33], v[166:169], v[34:37], v[18:33]
	ds_read_b128 v[192:195], v221 offset:4704
	v_add_f32_e32 v231, v231, v54
	v_add_f32_e32 v232, v232, v55
	v_add_f32_e32 v231, v231, v56
	v_add_f32_e32 v232, v232, v57
	s_waitcnt lgkmcnt(4)
	v_mfma_f32_32x32x16_bf16 v[2:17], v[170:173], v[42:45], v[2:17]
	v_cvt_pk_bf16_f32 v50, v50, v51
	v_cvt_pk_bf16_f32 v51, v52, v53
	v_cvt_pk_bf16_f32 v52, v54, v55
	v_cvt_pk_bf16_f32 v53, v56, v57
	v_exp_f32_e32 v58, v58
	v_mfma_f32_32x32x16_bf16 v[18:33], v[174:177], v[42:45], v[18:33]
	s_waitcnt vmcnt(4)
	ds_write_b64 v225, v[216:217] offset:18432
	ds_write_b64 v225, v[218:219] offset:18448
	v_exp_f32_e32 v59, v59
	v_exp_f32_e32 v60, v60
	v_exp_f32_e32 v61, v61
	s_waitcnt lgkmcnt(4)
	v_mfma_f32_32x32x16_bf16 v[2:17], v[180:183], v[50:53], v[2:17]
	v_add_f32_e32 v231, v231, v58
	v_add_f32_e32 v232, v232, v59
	v_exp_f32_e32 v62, v62
	v_mfma_f32_32x32x16_bf16 v[18:33], v[184:187], v[50:53], v[18:33]
	v_exp_f32_e32 v63, v63
	v_add_f32_e32 v231, v231, v60
	v_add_f32_e32 v232, v232, v61
	v_exp_f32_e32 v64, v64
	v_exp_f32_e32 v65, v65
	v_add_f32_e32 v231, v231, v62
	v_add_f32_e32 v232, v232, v63
	v_add_f32_e32 v231, v231, v64
	v_add_f32_e32 v232, v232, v65
	v_cvt_pk_bf16_f32 v58, v58, v59
	v_cvt_pk_bf16_f32 v59, v60, v61
	v_cvt_pk_bf16_f32 v60, v62, v63
	v_cvt_pk_bf16_f32 v61, v64, v65
	s_waitcnt lgkmcnt(2)
	s_nop 0
	v_mfma_f32_32x32x16_bf16 v[2:17], v[188:191], v[58:61], v[2:17]
	v_mfma_f32_32x32x16_bf16 v[18:33], v[192:195], v[58:61], v[18:33]
	ds_read_b128 v[138:141], v220 offset:26624
	ds_read_b128 v[142:145], v220 offset:33280
	ds_read_b128 v[146:149], v220 offset:26656
	ds_read_b128 v[150:153], v220 offset:33312
	ds_read_b128 v[154:157], v220 offset:26688
	ds_read_b128 v[158:161], v220 offset:33344
	s_waitcnt lgkmcnt(6)
	s_barrier
	v_exp_f32_e32 v66, v66
	v_exp_f32_e32 v67, v67
	v_exp_f32_e32 v68, v68
	s_waitcnt lgkmcnt(4)
	v_mfma_f32_32x32x16_bf16 v[34:49], v[138:141], v[98:101], v[122:137]
	ds_read_b128 v[138:141], v220 offset:26720
	v_exp_f32_e32 v69, v69
	v_add_f32_e32 v231, v231, v66
	v_add_f32_e32 v232, v232, v67
	v_exp_f32_e32 v70, v70
	v_mfma_f32_32x32x16_bf16 v[50:65], v[142:145], v[98:101], v[122:137]
	ds_read_b128 v[142:145], v220 offset:33376
	v_exp_f32_e32 v71, v71
	v_add_f32_e32 v231, v231, v68
	v_add_f32_e32 v232, v232, v69
	s_waitcnt lgkmcnt(4)
	v_mfma_f32_32x32x16_bf16 v[34:49], v[146:149], v[102:105], v[34:49]
	ds_read_b128 v[146:149], v220 offset:26752
	global_load_dwordx4 v[216:219], v229, s[10:11]
	s_add_u32 s10, s10, 0x80
	s_addc_u32 s11, s11, 0
	v_exp_f32_e32 v72, v72
	v_exp_f32_e32 v73, v73
	v_add_f32_e32 v231, v231, v70
	v_add_f32_e32 v232, v232, v71
	v_mfma_f32_32x32x16_bf16 v[50:65], v[150:153], v[102:105], v[50:65]
	ds_read_b128 v[150:153], v220 offset:33408
	v_add_f32_e32 v231, v231, v72
	v_add_f32_e32 v232, v232, v73
	v_cvt_pk_bf16_f32 v66, v66, v67
	v_cvt_pk_bf16_f32 v67, v68, v69
	v_cvt_pk_bf16_f32 v68, v70, v71
	s_waitcnt lgkmcnt(4)
	v_mfma_f32_32x32x16_bf16 v[34:49], v[154:157], v[106:109], v[34:49]
	ds_read_b128 v[154:157], v220 offset:26784
	v_cvt_pk_bf16_f32 v69, v72, v73
	v_exp_f32_e32 v74, v74
	v_exp_f32_e32 v75, v75
	v_mfma_f32_32x32x16_bf16 v[50:65], v[158:161], v[106:109], v[50:65]
	ds_read_b128 v[158:161], v220 offset:33440
	v_exp_f32_e32 v76, v76
	v_exp_f32_e32 v77, v77
	v_add_f32_e32 v231, v231, v74
	v_add_f32_e32 v232, v232, v75
	s_waitcnt lgkmcnt(4)
	v_mfma_f32_32x32x16_bf16 v[34:49], v[138:141], v[110:113], v[34:49]
	ds_read_b128 v[162:165], v221 offset:9216
	v_exp_f32_e32 v78, v78
	v_exp_f32_e32 v79, v79
	v_add_f32_e32 v231, v231, v76
	v_mfma_f32_32x32x16_bf16 v[50:65], v[142:145], v[110:113], v[50:65]
	ds_read_b128 v[166:169], v221 offset:13824
	v_add_f32_e32 v232, v232, v77
	v_exp_f32_e32 v80, v80
	v_exp_f32_e32 v81, v81
	s_waitcnt lgkmcnt(4)
	v_mfma_f32_32x32x16_bf16 v[34:49], v[146:149], v[114:117], v[34:49]
	ds_read_b128 v[170:173], v221 offset:9248
	v_add_f32_e32 v231, v231, v78
	v_add_f32_e32 v232, v232, v79
	v_add_f32_e32 v231, v231, v80
	v_add_f32_e32 v232, v232, v81
	v_cvt_pk_bf16_f32 v74, v74, v75
	v_cvt_pk_bf16_f32 v75, v76, v77
	v_mfma_f32_32x32x16_bf16 v[50:65], v[150:153], v[114:117], v[50:65]
	ds_read_b128 v[174:177], v221 offset:13856
	v_cvt_pk_bf16_f32 v76, v78, v79
	v_cvt_pk_bf16_f32 v77, v80, v81
	v_exp_f32_e32 v82, v82
	v_exp_f32_e32 v83, v83
	s_waitcnt lgkmcnt(4)
	v_mfma_f32_32x32x16_bf16 v[34:49], v[154:157], v[118:121], v[34:49]
	ds_read_b128 v[180:183], v221 offset:9280
	v_exp_f32_e32 v84, v84
	v_exp_f32_e32 v85, v85
	v_mfma_f32_32x32x16_bf16 v[50:65], v[158:161], v[118:121], v[50:65]
	ds_read_b128 v[184:187], v221 offset:13888
	v_add_f32_e32 v231, v231, v82
	v_add_f32_e32 v232, v232, v83
	v_exp_f32_e32 v86, v86
	v_exp_f32_e32 v87, v87
	s_waitcnt lgkmcnt(4)
	v_mfma_f32_32x32x16_bf16 v[2:17], v[162:165], v[66:69], v[2:17]
	ds_read_b128 v[188:191], v221 offset:9312
	v_add_f32_e32 v231, v231, v84
	v_add_f32_e32 v232, v232, v85
	v_exp_f32_e32 v88, v88
	v_exp_f32_e32 v89, v89
	v_mfma_f32_32x32x16_bf16 v[18:33], v[166:169], v[66:69], v[18:33]
	ds_read_b128 v[192:195], v221 offset:13920
	v_add_f32_e32 v231, v231, v86
	v_add_f32_e32 v232, v232, v87
	v_add_f32_e32 v231, v231, v88
	v_add_f32_e32 v232, v232, v89
	s_waitcnt lgkmcnt(4)
	v_mfma_f32_32x32x16_bf16 v[2:17], v[170:173], v[74:77], v[2:17]
	v_cvt_pk_bf16_f32 v82, v82, v83
	v_cvt_pk_bf16_f32 v83, v84, v85
	v_cvt_pk_bf16_f32 v84, v86, v87
	v_cvt_pk_bf16_f32 v85, v88, v89
	v_exp_f32_e32 v90, v90
	v_mfma_f32_32x32x16_bf16 v[18:33], v[174:177], v[74:77], v[18:33]
	s_waitcnt vmcnt(1)
	ds_write_b128 v222, v[200:203] offset:0
	ds_write_b128 v223, v[204:207] offset:0
	ds_write_b128 v224, v[208:211] offset:0
	ds_write_b64 v225, v[212:213] offset:27648
	ds_write_b64 v225, v[214:215] offset:27664
	v_exp_f32_e32 v91, v91
	v_exp_f32_e32 v92, v92
	v_exp_f32_e32 v93, v93
	s_waitcnt lgkmcnt(7)
	v_mfma_f32_32x32x16_bf16 v[2:17], v[180:183], v[82:85], v[2:17]
	v_add_f32_e32 v231, v231, v90
	v_add_f32_e32 v232, v232, v91
	v_exp_f32_e32 v94, v94
	v_mfma_f32_32x32x16_bf16 v[18:33], v[184:187], v[82:85], v[18:33]
	v_exp_f32_e32 v95, v95
	v_add_f32_e32 v231, v231, v92
	v_add_f32_e32 v232, v232, v93
	v_exp_f32_e32 v96, v96
	v_exp_f32_e32 v97, v97
	v_add_f32_e32 v231, v231, v94
	v_add_f32_e32 v232, v232, v95
	v_add_f32_e32 v231, v231, v96
	v_add_f32_e32 v232, v232, v97
	v_cvt_pk_bf16_f32 v90, v90, v91
	v_cvt_pk_bf16_f32 v91, v92, v93
	v_cvt_pk_bf16_f32 v92, v94, v95
	v_cvt_pk_bf16_f32 v93, v96, v97
	s_waitcnt lgkmcnt(5)
	s_nop 0
	v_mfma_f32_32x32x16_bf16 v[2:17], v[188:191], v[90:93], v[2:17]
	v_mfma_f32_32x32x16_bf16 v[18:33], v[192:195], v[90:93], v[18:33]
	ds_read_b128 v[138:141], v220 offset:39936
	ds_read_b128 v[142:145], v220 offset:46592
	ds_read_b128 v[146:149], v220 offset:39968
	ds_read_b128 v[150:153], v220 offset:46624
	ds_read_b128 v[154:157], v220 offset:40000
	ds_read_b128 v[158:161], v220 offset:46656
	s_waitcnt lgkmcnt(6)
	s_barrier
	v_exp_f32_e32 v34, v34
	v_exp_f32_e32 v35, v35
	v_exp_f32_e32 v36, v36
	s_waitcnt lgkmcnt(4)
	v_mfma_f32_32x32x16_bf16 v[66:81], v[138:141], v[98:101], v[122:137]
	ds_read_b128 v[138:141], v220 offset:40032
	v_exp_f32_e32 v37, v37
	v_add_f32_e32 v231, v231, v34
	v_add_f32_e32 v232, v232, v35
	v_exp_f32_e32 v38, v38
	v_mfma_f32_32x32x16_bf16 v[82:97], v[142:145], v[98:101], v[122:137]
	ds_read_b128 v[142:145], v220 offset:46688
	v_exp_f32_e32 v39, v39
	v_add_f32_e32 v231, v231, v36
	v_add_f32_e32 v232, v232, v37
	s_waitcnt lgkmcnt(4)
	v_mfma_f32_32x32x16_bf16 v[66:81], v[146:149], v[102:105], v[66:81]
	ds_read_b128 v[146:149], v220 offset:40064
	global_load_dwordx4 v[200:203], v226, s[4:5]
	global_load_dwordx4 v[204:207], v227, s[4:5]
	global_load_dwordx4 v[208:211], v228, s[4:5]
	s_add_u32 s4, s4, 0x6000
	s_addc_u32 s5, s5, 0
	global_load_dwordx4 v[212:215], v229, s[10:11]
	s_add_u32 s10, s10, 0x80
	s_addc_u32 s11, s11, 0
	v_exp_f32_e32 v40, v40
	v_exp_f32_e32 v41, v41
	v_add_f32_e32 v231, v231, v38
	v_add_f32_e32 v232, v232, v39
	v_mfma_f32_32x32x16_bf16 v[82:97], v[150:153], v[102:105], v[82:97]
	ds_read_b128 v[150:153], v220 offset:46720
	v_add_f32_e32 v231, v231, v40
	v_add_f32_e32 v232, v232, v41
	v_cvt_pk_bf16_f32 v34, v34, v35
	v_cvt_pk_bf16_f32 v35, v36, v37
	v_cvt_pk_bf16_f32 v36, v38, v39
	s_waitcnt lgkmcnt(4)
	v_mfma_f32_32x32x16_bf16 v[66:81], v[154:157], v[106:109], v[66:81]
	ds_read_b128 v[154:157], v220 offset:40096
	v_cvt_pk_bf16_f32 v37, v40, v41
	v_exp_f32_e32 v42, v42
	v_exp_f32_e32 v43, v43
	v_mfma_f32_32x32x16_bf16 v[82:97], v[158:161], v[106:109], v[82:97]
	ds_read_b128 v[158:161], v220 offset:46752
	v_exp_f32_e32 v44, v44
	v_exp_f32_e32 v45, v45
	v_add_f32_e32 v231, v231, v42
	v_add_f32_e32 v232, v232, v43
	s_waitcnt lgkmcnt(4)
	v_mfma_f32_32x32x16_bf16 v[66:81], v[138:141], v[110:113], v[66:81]
	ds_read_b128 v[162:165], v221 offset:18432
	v_exp_f32_e32 v46, v46
	v_exp_f32_e32 v47, v47
	v_add_f32_e32 v231, v231, v44
	v_mfma_f32_32x32x16_bf16 v[82:97], v[142:145], v[110:113], v[82:97]
	ds_read_b128 v[166:169], v221 offset:23040
	v_add_f32_e32 v232, v232, v45
	v_exp_f32_e32 v48, v48
	v_exp_f32_e32 v49, v49
	s_waitcnt lgkmcnt(4)
	v_mfma_f32_32x32x16_bf16 v[66:81], v[146:149], v[114:117], v[66:81]
	ds_read_b128 v[170:173], v221 offset:18464
	v_add_f32_e32 v231, v231, v46
	v_add_f32_e32 v232, v232, v47
	v_add_f32_e32 v231, v231, v48
	v_add_f32_e32 v232, v232, v49
	v_cvt_pk_bf16_f32 v42, v42, v43
	v_cvt_pk_bf16_f32 v43, v44, v45
	v_mfma_f32_32x32x16_bf16 v[82:97], v[150:153], v[114:117], v[82:97]
	ds_read_b128 v[174:177], v221 offset:23072
	v_cvt_pk_bf16_f32 v44, v46, v47
	v_cvt_pk_bf16_f32 v45, v48, v49
	v_exp_f32_e32 v50, v50
	v_exp_f32_e32 v51, v51
	s_waitcnt lgkmcnt(4)
	v_mfma_f32_32x32x16_bf16 v[66:81], v[154:157], v[118:121], v[66:81]
	ds_read_b128 v[180:183], v221 offset:18496
	v_exp_f32_e32 v52, v52
	v_exp_f32_e32 v53, v53
	v_mfma_f32_32x32x16_bf16 v[82:97], v[158:161], v[118:121], v[82:97]
	ds_read_b128 v[184:187], v221 offset:23104
	v_add_f32_e32 v231, v231, v50
	v_add_f32_e32 v232, v232, v51
	v_exp_f32_e32 v54, v54
	v_exp_f32_e32 v55, v55
	s_waitcnt lgkmcnt(4)
	v_mfma_f32_32x32x16_bf16 v[2:17], v[162:165], v[34:37], v[2:17]
	ds_read_b128 v[188:191], v221 offset:18528
	v_add_f32_e32 v231, v231, v52
	v_add_f32_e32 v232, v232, v53
	v_exp_f32_e32 v56, v56
	v_exp_f32_e32 v57, v57
	v_mfma_f32_32x32x16_bf16 v[18:33], v[166:169], v[34:37], v[18:33]
	ds_read_b128 v[192:195], v221 offset:23136
	v_add_f32_e32 v231, v231, v54
	v_add_f32_e32 v232, v232, v55
	v_add_f32_e32 v231, v231, v56
	v_add_f32_e32 v232, v232, v57
	s_waitcnt lgkmcnt(4)
	v_mfma_f32_32x32x16_bf16 v[2:17], v[170:173], v[42:45], v[2:17]
	v_cvt_pk_bf16_f32 v50, v50, v51
	v_cvt_pk_bf16_f32 v51, v52, v53
	v_cvt_pk_bf16_f32 v52, v54, v55
	v_cvt_pk_bf16_f32 v53, v56, v57
	v_exp_f32_e32 v58, v58
	v_mfma_f32_32x32x16_bf16 v[18:33], v[174:177], v[42:45], v[18:33]
	s_waitcnt vmcnt(4)
	ds_write_b64 v225, v[216:217] offset:0
	ds_write_b64 v225, v[218:219] offset:16
	v_exp_f32_e32 v59, v59
	v_exp_f32_e32 v60, v60
	v_exp_f32_e32 v61, v61
	s_waitcnt lgkmcnt(4)
	v_mfma_f32_32x32x16_bf16 v[2:17], v[180:183], v[50:53], v[2:17]
	v_add_f32_e32 v231, v231, v58
	v_add_f32_e32 v232, v232, v59
	v_exp_f32_e32 v62, v62
	v_mfma_f32_32x32x16_bf16 v[18:33], v[184:187], v[50:53], v[18:33]
	v_exp_f32_e32 v63, v63
	v_add_f32_e32 v231, v231, v60
	v_add_f32_e32 v232, v232, v61
	v_exp_f32_e32 v64, v64
	v_exp_f32_e32 v65, v65
	v_add_f32_e32 v231, v231, v62
	v_add_f32_e32 v232, v232, v63
	v_add_f32_e32 v231, v231, v64
	v_add_f32_e32 v232, v232, v65
	v_cvt_pk_bf16_f32 v58, v58, v59
	v_cvt_pk_bf16_f32 v59, v60, v61
	v_cvt_pk_bf16_f32 v60, v62, v63
	v_cvt_pk_bf16_f32 v61, v64, v65
	s_waitcnt lgkmcnt(2)
	s_nop 0
	v_mfma_f32_32x32x16_bf16 v[2:17], v[188:191], v[58:61], v[2:17]
	v_mfma_f32_32x32x16_bf16 v[18:33], v[192:195], v[58:61], v[18:33]
	ds_read_b128 v[138:141], v220 offset:0
	ds_read_b128 v[142:145], v220 offset:6656
	ds_read_b128 v[146:149], v220 offset:32
	ds_read_b128 v[150:153], v220 offset:6688
	ds_read_b128 v[154:157], v220 offset:64
	ds_read_b128 v[158:161], v220 offset:6720
	s_waitcnt lgkmcnt(6)
	s_barrier
	v_exp_f32_e32 v66, v66
	v_exp_f32_e32 v67, v67
	v_exp_f32_e32 v68, v68
	s_waitcnt lgkmcnt(4)
	v_mfma_f32_32x32x16_bf16 v[34:49], v[138:141], v[98:101], v[122:137]
	ds_read_b128 v[138:141], v220 offset:96
	v_exp_f32_e32 v69, v69
	v_add_f32_e32 v231, v231, v66
	v_add_f32_e32 v232, v232, v67
	v_exp_f32_e32 v70, v70
	v_mfma_f32_32x32x16_bf16 v[50:65], v[142:145], v[98:101], v[122:137]
	ds_read_b128 v[142:145], v220 offset:6752
	v_exp_f32_e32 v71, v71
	v_add_f32_e32 v231, v231, v68
	v_add_f32_e32 v232, v232, v69
	s_waitcnt lgkmcnt(4)
	v_mfma_f32_32x32x16_bf16 v[34:49], v[146:149], v[102:105], v[34:49]
	ds_read_b128 v[146:149], v220 offset:128
	global_load_dwordx4 v[216:219], v229, s[10:11]
	s_add_u32 s10, s10, 0x80
	s_addc_u32 s11, s11, 0
	v_exp_f32_e32 v72, v72
	v_exp_f32_e32 v73, v73
	v_add_f32_e32 v231, v231, v70
	v_add_f32_e32 v232, v232, v71
	v_mfma_f32_32x32x16_bf16 v[50:65], v[150:153], v[102:105], v[50:65]
	ds_read_b128 v[150:153], v220 offset:6784
	v_add_f32_e32 v231, v231, v72
	v_add_f32_e32 v232, v232, v73
	v_cvt_pk_bf16_f32 v66, v66, v67
	v_cvt_pk_bf16_f32 v67, v68, v69
	v_cvt_pk_bf16_f32 v68, v70, v71
	s_waitcnt lgkmcnt(4)
	v_mfma_f32_32x32x16_bf16 v[34:49], v[154:157], v[106:109], v[34:49]
	ds_read_b128 v[154:157], v220 offset:160
	v_cvt_pk_bf16_f32 v69, v72, v73
	v_exp_f32_e32 v74, v74
	v_exp_f32_e32 v75, v75
	v_mfma_f32_32x32x16_bf16 v[50:65], v[158:161], v[106:109], v[50:65]
	ds_read_b128 v[158:161], v220 offset:6816
	v_exp_f32_e32 v76, v76
	v_exp_f32_e32 v77, v77
	v_add_f32_e32 v231, v231, v74
	v_add_f32_e32 v232, v232, v75
	s_waitcnt lgkmcnt(4)
	v_mfma_f32_32x32x16_bf16 v[34:49], v[138:141], v[110:113], v[34:49]
	ds_read_b128 v[162:165], v221 offset:27648
	v_exp_f32_e32 v78, v78
	v_exp_f32_e32 v79, v79
	v_add_f32_e32 v231, v231, v76
	v_mfma_f32_32x32x16_bf16 v[50:65], v[142:145], v[110:113], v[50:65]
	ds_read_b128 v[166:169], v221 offset:32256
	v_add_f32_e32 v232, v232, v77
	v_exp_f32_e32 v80, v80
	v_exp_f32_e32 v81, v81
	s_waitcnt lgkmcnt(4)
	v_mfma_f32_32x32x16_bf16 v[34:49], v[146:149], v[114:117], v[34:49]
	ds_read_b128 v[170:173], v221 offset:27680
	v_add_f32_e32 v231, v231, v78
	v_add_f32_e32 v232, v232, v79
	v_add_f32_e32 v231, v231, v80
	v_add_f32_e32 v232, v232, v81
	v_cvt_pk_bf16_f32 v74, v74, v75
	v_cvt_pk_bf16_f32 v75, v76, v77
	v_mfma_f32_32x32x16_bf16 v[50:65], v[150:153], v[114:117], v[50:65]
	ds_read_b128 v[174:177], v221 offset:32288
	v_cvt_pk_bf16_f32 v76, v78, v79
	v_cvt_pk_bf16_f32 v77, v80, v81
	v_exp_f32_e32 v82, v82
	v_exp_f32_e32 v83, v83
	s_waitcnt lgkmcnt(4)
	v_mfma_f32_32x32x16_bf16 v[34:49], v[154:157], v[118:121], v[34:49]
	ds_read_b128 v[180:183], v221 offset:27712
	v_exp_f32_e32 v84, v84
	v_exp_f32_e32 v85, v85
	v_mfma_f32_32x32x16_bf16 v[50:65], v[158:161], v[118:121], v[50:65]
	ds_read_b128 v[184:187], v221 offset:32320
	v_add_f32_e32 v231, v231, v82
	v_add_f32_e32 v232, v232, v83
	v_exp_f32_e32 v86, v86
	v_exp_f32_e32 v87, v87
	s_waitcnt lgkmcnt(4)
	v_mfma_f32_32x32x16_bf16 v[2:17], v[162:165], v[66:69], v[2:17]
	ds_read_b128 v[188:191], v221 offset:27744
	v_add_f32_e32 v231, v231, v84
	v_add_f32_e32 v232, v232, v85
	v_exp_f32_e32 v88, v88
	v_exp_f32_e32 v89, v89
	v_mfma_f32_32x32x16_bf16 v[18:33], v[166:169], v[66:69], v[18:33]
	ds_read_b128 v[192:195], v221 offset:32352
	v_add_f32_e32 v231, v231, v86
	v_add_f32_e32 v232, v232, v87
	v_add_f32_e32 v231, v231, v88
	v_add_f32_e32 v232, v232, v89
	s_waitcnt lgkmcnt(4)
	v_mfma_f32_32x32x16_bf16 v[2:17], v[170:173], v[74:77], v[2:17]
	v_cvt_pk_bf16_f32 v82, v82, v83
	v_cvt_pk_bf16_f32 v83, v84, v85
	v_cvt_pk_bf16_f32 v84, v86, v87
	v_cvt_pk_bf16_f32 v85, v88, v89
	v_exp_f32_e32 v90, v90
	v_mfma_f32_32x32x16_bf16 v[18:33], v[174:177], v[74:77], v[18:33]
	s_waitcnt vmcnt(1)
	ds_write_b128 v222, v[200:203] offset:26624
	ds_write_b128 v223, v[204:207] offset:26624
	ds_write_b128 v224, v[208:211] offset:26624
	ds_write_b64 v225, v[212:213] offset:9216
	ds_write_b64 v225, v[214:215] offset:9232
	v_exp_f32_e32 v91, v91
	v_exp_f32_e32 v92, v92
	v_exp_f32_e32 v93, v93
	s_waitcnt lgkmcnt(7)
	v_mfma_f32_32x32x16_bf16 v[2:17], v[180:183], v[82:85], v[2:17]
	v_add_f32_e32 v231, v231, v90
	v_add_f32_e32 v232, v232, v91
	v_exp_f32_e32 v94, v94
	v_mfma_f32_32x32x16_bf16 v[18:33], v[184:187], v[82:85], v[18:33]
	v_exp_f32_e32 v95, v95
	v_add_f32_e32 v231, v231, v92
	v_add_f32_e32 v232, v232, v93
	v_exp_f32_e32 v96, v96
	v_exp_f32_e32 v97, v97
	v_add_f32_e32 v231, v231, v94
	v_add_f32_e32 v232, v232, v95
	v_add_f32_e32 v231, v231, v96
	v_add_f32_e32 v232, v232, v97
	v_cvt_pk_bf16_f32 v90, v90, v91
	v_cvt_pk_bf16_f32 v91, v92, v93
	v_cvt_pk_bf16_f32 v92, v94, v95
	v_cvt_pk_bf16_f32 v93, v96, v97
	s_waitcnt lgkmcnt(5)
	s_nop 0
	v_mfma_f32_32x32x16_bf16 v[2:17], v[188:191], v[90:93], v[2:17]
	v_mfma_f32_32x32x16_bf16 v[18:33], v[192:195], v[90:93], v[18:33]
	ds_read_b128 v[138:141], v220 offset:13312
	ds_read_b128 v[142:145], v220 offset:19968
	ds_read_b128 v[146:149], v220 offset:13344
	ds_read_b128 v[150:153], v220 offset:20000
	ds_read_b128 v[154:157], v220 offset:13376
	ds_read_b128 v[158:161], v220 offset:20032
	s_waitcnt lgkmcnt(6)
	s_barrier
	s_add_i32 s16, s16, -1
	s_cmp_lg_u32 s16, 0
	s_cbranch_scc1 .Lmla_loop
	v_exp_f32_e32 v34, v34
	v_exp_f32_e32 v35, v35
	v_exp_f32_e32 v36, v36
	s_waitcnt lgkmcnt(4)
	v_mfma_f32_32x32x16_bf16 v[66:81], v[138:141], v[98:101], v[122:137]
	ds_read_b128 v[138:141], v220 offset:13408
	v_exp_f32_e32 v37, v37
	v_add_f32_e32 v231, v231, v34
	v_add_f32_e32 v232, v232, v35
	v_exp_f32_e32 v38, v38
	v_mfma_f32_32x32x16_bf16 v[82:97], v[142:145], v[98:101], v[122:137]
	ds_read_b128 v[142:145], v220 offset:20064
	v_exp_f32_e32 v39, v39
	v_add_f32_e32 v231, v231, v36
	v_add_f32_e32 v232, v232, v37
	s_waitcnt lgkmcnt(4)
	v_mfma_f32_32x32x16_bf16 v[66:81], v[146:149], v[102:105], v[66:81]
	ds_read_b128 v[146:149], v220 offset:13440
	global_load_dwordx4 v[212:215], v229, s[10:11]
	s_add_u32 s10, s10, 0x80
	s_addc_u32 s11, s11, 0
	v_exp_f32_e32 v40, v40
	v_exp_f32_e32 v41, v41
	v_add_f32_e32 v231, v231, v38
	v_add_f32_e32 v232, v232, v39
	v_mfma_f32_32x32x16_bf16 v[82:97], v[150:153], v[102:105], v[82:97]
	ds_read_b128 v[150:153], v220 offset:20096
	v_add_f32_e32 v231, v231, v40
	v_add_f32_e32 v232, v232, v41
	v_cvt_pk_bf16_f32 v34, v34, v35
	v_cvt_pk_bf16_f32 v35, v36, v37
	v_cvt_pk_bf16_f32 v36, v38, v39
	s_waitcnt lgkmcnt(4)
	v_mfma_f32_32x32x16_bf16 v[66:81], v[154:157], v[106:109], v[66:81]
	ds_read_b128 v[154:157], v220 offset:13472
	v_cvt_pk_bf16_f32 v37, v40, v41
	v_exp_f32_e32 v42, v42
	v_exp_f32_e32 v43, v43
	v_mfma_f32_32x32x16_bf16 v[82:97], v[158:161], v[106:109], v[82:97]
	ds_read_b128 v[158:161], v220 offset:20128
	v_exp_f32_e32 v44, v44
	v_exp_f32_e32 v45, v45
	v_add_f32_e32 v231, v231, v42
	v_add_f32_e32 v232, v232, v43
	s_waitcnt lgkmcnt(4)
	v_mfma_f32_32x32x16_bf16 v[66:81], v[138:141], v[110:113], v[66:81]
	ds_read_b128 v[162:165], v221 offset:0
	v_exp_f32_e32 v46, v46
	v_exp_f32_e32 v47, v47
	v_add_f32_e32 v231, v231, v44
	v_mfma_f32_32x32x16_bf16 v[82:97], v[142:145], v[110:113], v[82:97]
	ds_read_b128 v[166:169], v221 offset:4608
	v_add_f32_e32 v232, v232, v45
	v_exp_f32_e32 v48, v48
	v_exp_f32_e32 v49, v49
	s_waitcnt lgkmcnt(4)
	v_mfma_f32_32x32x16_bf16 v[66:81], v[146:149], v[114:117], v[66:81]
	ds_read_b128 v[170:173], v221 offset:32
	v_add_f32_e32 v231, v231, v46
	v_add_f32_e32 v232, v232, v47
	v_add_f32_e32 v231, v231, v48
	v_add_f32_e32 v232, v232, v49
	v_cvt_pk_bf16_f32 v42, v42, v43
	v_cvt_pk_bf16_f32 v43, v44, v45
	v_mfma_f32_32x32x16_bf16 v[82:97], v[150:153], v[114:117], v[82:97]
	ds_read_b128 v[174:177], v221 offset:4640
	v_cvt_pk_bf16_f32 v44, v46, v47
	v_cvt_pk_bf16_f32 v45, v48, v49
	v_exp_f32_e32 v50, v50
	v_exp_f32_e32 v51, v51
	s_waitcnt lgkmcnt(4)
	v_mfma_f32_32x32x16_bf16 v[66:81], v[154:157], v[118:121], v[66:81]
	ds_read_b128 v[180:183], v221 offset:64
	v_exp_f32_e32 v52, v52
	v_exp_f32_e32 v53, v53
	v_mfma_f32_32x32x16_bf16 v[82:97], v[158:161], v[118:121], v[82:97]
	ds_read_b128 v[184:187], v221 offset:4672
	v_add_f32_e32 v231, v231, v50
	v_add_f32_e32 v232, v232, v51
	v_exp_f32_e32 v54, v54
	v_exp_f32_e32 v55, v55
	s_waitcnt lgkmcnt(4)
	v_mfma_f32_32x32x16_bf16 v[2:17], v[162:165], v[34:37], v[2:17]
	ds_read_b128 v[188:191], v221 offset:96
	v_add_f32_e32 v231, v231, v52
	v_add_f32_e32 v232, v232, v53
	v_exp_f32_e32 v56, v56
	v_exp_f32_e32 v57, v57
	v_mfma_f32_32x32x16_bf16 v[18:33], v[166:169], v[34:37], v[18:33]
	ds_read_b128 v[192:195], v221 offset:4704
	v_add_f32_e32 v231, v231, v54
	v_add_f32_e32 v232, v232, v55
	v_add_f32_e32 v231, v231, v56
	v_add_f32_e32 v232, v232, v57
	s_waitcnt lgkmcnt(4)
	v_mfma_f32_32x32x16_bf16 v[2:17], v[170:173], v[42:45], v[2:17]
	v_cvt_pk_bf16_f32 v50, v50, v51
	v_cvt_pk_bf16_f32 v51, v52, v53
	v_cvt_pk_bf16_f32 v52, v54, v55
	v_cvt_pk_bf16_f32 v53, v56, v57
	v_exp_f32_e32 v58, v58
	v_mfma_f32_32x32x16_bf16 v[18:33], v[174:177], v[42:45], v[18:33]
	s_waitcnt vmcnt(1)
	ds_write_b64 v225, v[216:217] offset:18432
	ds_write_b64 v225, v[218:219] offset:18448
	v_exp_f32_e32 v59, v59
	v_exp_f32_e32 v60, v60
	v_exp_f32_e32 v61, v61
	s_waitcnt lgkmcnt(4)
	v_mfma_f32_32x32x16_bf16 v[2:17], v[180:183], v[50:53], v[2:17]
	v_add_f32_e32 v231, v231, v58
	v_add_f32_e32 v232, v232, v59
	v_exp_f32_e32 v62, v62
	v_mfma_f32_32x32x16_bf16 v[18:33], v[184:187], v[50:53], v[18:33]
	v_exp_f32_e32 v63, v63
	v_add_f32_e32 v231, v231, v60
	v_add_f32_e32 v232, v232, v61
	v_exp_f32_e32 v64, v64
	v_exp_f32_e32 v65, v65
	v_add_f32_e32 v231, v231, v62
	v_add_f32_e32 v232, v232, v63
	v_add_f32_e32 v231, v231, v64
	v_add_f32_e32 v232, v232, v65
	v_cvt_pk_bf16_f32 v58, v58, v59
	v_cvt_pk_bf16_f32 v59, v60, v61
	v_cvt_pk_bf16_f32 v60, v62, v63
	v_cvt_pk_bf16_f32 v61, v64, v65
	s_waitcnt lgkmcnt(2)
	s_nop 0
	v_mfma_f32_32x32x16_bf16 v[2:17], v[188:191], v[58:61], v[2:17]
	v_mfma_f32_32x32x16_bf16 v[18:33], v[192:195], v[58:61], v[18:33]
	ds_read_b128 v[138:141], v220 offset:26624
	ds_read_b128 v[142:145], v220 offset:33280
	ds_read_b128 v[146:149], v220 offset:26656
	ds_read_b128 v[150:153], v220 offset:33312
	ds_read_b128 v[154:157], v220 offset:26688
	ds_read_b128 v[158:161], v220 offset:33344
	s_waitcnt lgkmcnt(6)
	s_barrier
	v_exp_f32_e32 v66, v66
	v_exp_f32_e32 v67, v67
	v_exp_f32_e32 v68, v68
	s_waitcnt lgkmcnt(4)
	v_mfma_f32_32x32x16_bf16 v[34:49], v[138:141], v[98:101], v[122:137]
	ds_read_b128 v[138:141], v220 offset:26720
	v_exp_f32_e32 v69, v69
	v_add_f32_e32 v231, v231, v66
	v_add_f32_e32 v232, v232, v67
	v_exp_f32_e32 v70, v70
	v_mfma_f32_32x32x16_bf16 v[50:65], v[142:145], v[98:101], v[122:137]
	ds_read_b128 v[142:145], v220 offset:33376
	v_exp_f32_e32 v71, v71
	v_add_f32_e32 v231, v231, v68
	v_add_f32_e32 v232, v232, v69
	s_waitcnt lgkmcnt(4)
	v_mfma_f32_32x32x16_bf16 v[34:49], v[146:149], v[102:105], v[34:49]
	ds_read_b128 v[146:149], v220 offset:26752
	v_exp_f32_e32 v72, v72
	v_exp_f32_e32 v73, v73
	v_add_f32_e32 v231, v231, v70
	v_add_f32_e32 v232, v232, v71
	v_mfma_f32_32x32x16_bf16 v[50:65], v[150:153], v[102:105], v[50:65]
	ds_read_b128 v[150:153], v220 offset:33408
	v_add_f32_e32 v231, v231, v72
	v_add_f32_e32 v232, v232, v73
	v_cvt_pk_bf16_f32 v66, v66, v67
	v_cvt_pk_bf16_f32 v67, v68, v69
	v_cvt_pk_bf16_f32 v68, v70, v71
	s_waitcnt lgkmcnt(4)
	v_mfma_f32_32x32x16_bf16 v[34:49], v[154:157], v[106:109], v[34:49]
	ds_read_b128 v[154:157], v220 offset:26784
	v_cvt_pk_bf16_f32 v69, v72, v73
	v_exp_f32_e32 v74, v74
	v_exp_f32_e32 v75, v75
	v_mfma_f32_32x32x16_bf16 v[50:65], v[158:161], v[106:109], v[50:65]
	ds_read_b128 v[158:161], v220 offset:33440
	v_exp_f32_e32 v76, v76
	v_exp_f32_e32 v77, v77
	v_add_f32_e32 v231, v231, v74
	v_add_f32_e32 v232, v232, v75
	s_waitcnt lgkmcnt(4)
	v_mfma_f32_32x32x16_bf16 v[34:49], v[138:141], v[110:113], v[34:49]
	ds_read_b128 v[162:165], v221 offset:9216
	v_exp_f32_e32 v78, v78
	v_exp_f32_e32 v79, v79
	v_add_f32_e32 v231, v231, v76
	v_mfma_f32_32x32x16_bf16 v[50:65], v[142:145], v[110:113], v[50:65]
	ds_read_b128 v[166:169], v221 offset:13824
	v_add_f32_e32 v232, v232, v77
	v_exp_f32_e32 v80, v80
	v_exp_f32_e32 v81, v81
	s_waitcnt lgkmcnt(4)
	v_mfma_f32_32x32x16_bf16 v[34:49], v[146:149], v[114:117], v[34:49]
	ds_read_b128 v[170:173], v221 offset:9248
	v_add_f32_e32 v231, v231, v78
	v_add_f32_e32 v232, v232, v79
	v_add_f32_e32 v231, v231, v80
	v_add_f32_e32 v232, v232, v81
	v_cvt_pk_bf16_f32 v74, v74, v75
	v_cvt_pk_bf16_f32 v75, v76, v77
	v_mfma_f32_32x32x16_bf16 v[50:65], v[150:153], v[114:117], v[50:65]
	ds_read_b128 v[174:177], v221 offset:13856
	v_cvt_pk_bf16_f32 v76, v78, v79
	v_cvt_pk_bf16_f32 v77, v80, v81
	v_exp_f32_e32 v82, v82
	v_exp_f32_e32 v83, v83
	s_waitcnt lgkmcnt(4)
	v_mfma_f32_32x32x16_bf16 v[34:49], v[154:157], v[118:121], v[34:49]
	ds_read_b128 v[180:183], v221 offset:9280
	v_exp_f32_e32 v84, v84
	v_exp_f32_e32 v85, v85
	v_mfma_f32_32x32x16_bf16 v[50:65], v[158:161], v[118:121], v[50:65]
	ds_read_b128 v[184:187], v221 offset:13888
	v_add_f32_e32 v231, v231, v82
	v_add_f32_e32 v232, v232, v83
	v_exp_f32_e32 v86, v86
	v_exp_f32_e32 v87, v87
	s_waitcnt lgkmcnt(4)
	v_mfma_f32_32x32x16_bf16 v[2:17], v[162:165], v[66:69], v[2:17]
	ds_read_b128 v[188:191], v221 offset:9312
	v_add_f32_e32 v231, v231, v84
	v_add_f32_e32 v232, v232, v85
	v_exp_f32_e32 v88, v88
	v_exp_f32_e32 v89, v89
	v_mfma_f32_32x32x16_bf16 v[18:33], v[166:169], v[66:69], v[18:33]
	ds_read_b128 v[192:195], v221 offset:13920
	v_add_f32_e32 v231, v231, v86
	v_add_f32_e32 v232, v232, v87
	v_add_f32_e32 v231, v231, v88
	v_add_f32_e32 v232, v232, v89
	s_waitcnt lgkmcnt(4)
	v_mfma_f32_32x32x16_bf16 v[2:17], v[170:173], v[74:77], v[2:17]
	v_cvt_pk_bf16_f32 v82, v82, v83
	v_cvt_pk_bf16_f32 v83, v84, v85
	v_cvt_pk_bf16_f32 v84, v86, v87
	v_cvt_pk_bf16_f32 v85, v88, v89
	v_exp_f32_e32 v90, v90
	v_mfma_f32_32x32x16_bf16 v[18:33], v[174:177], v[74:77], v[18:33]
	s_waitcnt vmcnt(0)
	ds_write_b64 v225, v[212:213] offset:27648
	ds_write_b64 v225, v[214:215] offset:27664
	v_exp_f32_e32 v91, v91
	v_exp_f32_e32 v92, v92
	v_exp_f32_e32 v93, v93
	s_waitcnt lgkmcnt(4)
	v_mfma_f32_32x32x16_bf16 v[2:17], v[180:183], v[82:85], v[2:17]
	v_add_f32_e32 v231, v231, v90
	v_add_f32_e32 v232, v232, v91
	v_exp_f32_e32 v94, v94
	v_mfma_f32_32x32x16_bf16 v[18:33], v[184:187], v[82:85], v[18:33]
	v_exp_f32_e32 v95, v95
	v_add_f32_e32 v231, v231, v92
	v_add_f32_e32 v232, v232, v93
	v_exp_f32_e32 v96, v96
	v_exp_f32_e32 v97, v97
	v_add_f32_e32 v231, v231, v94
	v_add_f32_e32 v232, v232, v95
	v_add_f32_e32 v231, v231, v96
	v_add_f32_e32 v232, v232, v97
	v_cvt_pk_bf16_f32 v90, v90, v91
	v_cvt_pk_bf16_f32 v91, v92, v93
	v_cvt_pk_bf16_f32 v92, v94, v95
	v_cvt_pk_bf16_f32 v93, v96, v97
	s_waitcnt lgkmcnt(2)
	s_nop 0
	v_mfma_f32_32x32x16_bf16 v[2:17], v[188:191], v[90:93], v[2:17]
	v_mfma_f32_32x32x16_bf16 v[18:33], v[192:195], v[90:93], v[18:33]
	ds_read_b128 v[138:141], v220 offset:39936
	ds_read_b128 v[142:145], v220 offset:46592
	ds_read_b128 v[146:149], v220 offset:39968
	ds_read_b128 v[150:153], v220 offset:46624
	ds_read_b128 v[154:157], v220 offset:40000
	ds_read_b128 v[158:161], v220 offset:46656
	s_waitcnt lgkmcnt(6)
	s_barrier
	global_load_dwordx2 v[200:201], v236, s[14:15] offset:0
	global_load_dwordx2 v[202:203], v236, s[14:15] offset:16
	global_load_dwordx2 v[204:205], v236, s[14:15] offset:32
	global_load_dwordx2 v[206:207], v236, s[14:15] offset:48
	global_load_dwordx2 v[208:209], v236, s[14:15] offset:64
	global_load_dwordx2 v[210:211], v236, s[14:15] offset:80
	global_load_dwordx2 v[212:213], v236, s[14:15] offset:96
	global_load_dwordx2 v[214:215], v236, s[14:15] offset:112
	v_exp_f32_e32 v34, v34
	v_exp_f32_e32 v35, v35
	v_exp_f32_e32 v36, v36
	s_waitcnt lgkmcnt(4)
	v_mfma_f32_32x32x16_bf16 v[66:81], v[138:141], v[98:101], v[122:137]
	ds_read_b128 v[138:141], v220 offset:40032
	v_exp_f32_e32 v37, v37
	v_add_f32_e32 v231, v231, v34
	v_add_f32_e32 v232, v232, v35
	v_exp_f32_e32 v38, v38
	v_mfma_f32_32x32x16_bf16 v[82:97], v[142:145], v[98:101], v[122:137]
	ds_read_b128 v[142:145], v220 offset:46688
	v_exp_f32_e32 v39, v39
	v_add_f32_e32 v231, v231, v36
	v_add_f32_e32 v232, v232, v37
	s_waitcnt lgkmcnt(4)
	v_mfma_f32_32x32x16_bf16 v[66:81], v[146:149], v[102:105], v[66:81]
	ds_read_b128 v[146:149], v220 offset:40064
	v_exp_f32_e32 v40, v40
	v_exp_f32_e32 v41, v41
	v_add_f32_e32 v231, v231, v38
	v_add_f32_e32 v232, v232, v39
	v_mfma_f32_32x32x16_bf16 v[82:97], v[150:153], v[102:105], v[82:97]
	ds_read_b128 v[150:153], v220 offset:46720
	v_add_f32_e32 v231, v231, v40
	v_add_f32_e32 v232, v232, v41
	v_cvt_pk_bf16_f32 v34, v34, v35
	v_cvt_pk_bf16_f32 v35, v36, v37
	v_cvt_pk_bf16_f32 v36, v38, v39
	s_waitcnt lgkmcnt(4)
	v_mfma_f32_32x32x16_bf16 v[66:81], v[154:157], v[106:109], v[66:81]
	ds_read_b128 v[154:157], v220 offset:40096
	v_cvt_pk_bf16_f32 v37, v40, v41
	v_exp_f32_e32 v42, v42
	v_exp_f32_e32 v43, v43
	v_mfma_f32_32x32x16_bf16 v[82:97], v[158:161], v[106:109], v[82:97]
	ds_read_b128 v[158:161], v220 offset:46752
	v_exp_f32_e32 v44, v44
	v_exp_f32_e32 v45, v45
	v_add_f32_e32 v231, v231, v42
	v_add_f32_e32 v232, v232, v43
	s_waitcnt lgkmcnt(4)
	v_mfma_f32_32x32x16_bf16 v[66:81], v[138:141], v[110:113], v[66:81]
	ds_read_b128 v[162:165], v221 offset:18432
	v_exp_f32_e32 v46, v46
	v_exp_f32_e32 v47, v47
	v_add_f32_e32 v231, v231, v44
	v_mfma_f32_32x32x16_bf16 v[82:97], v[142:145], v[110:113], v[82:97]
	ds_read_b128 v[166:169], v221 offset:23040
	v_add_f32_e32 v232, v232, v45
	v_exp_f32_e32 v48, v48
	v_exp_f32_e32 v49, v49
	s_waitcnt lgkmcnt(4)
	v_mfma_f32_32x32x16_bf16 v[66:81], v[146:149], v[114:117], v[66:81]
	ds_read_b128 v[170:173], v221 offset:18464
	v_add_f32_e32 v231, v231, v46
	v_add_f32_e32 v232, v232, v47
	v_add_f32_e32 v231, v231, v48
	v_add_f32_e32 v232, v232, v49
	v_cvt_pk_bf16_f32 v42, v42, v43
	v_cvt_pk_bf16_f32 v43, v44, v45
	v_mfma_f32_32x32x16_bf16 v[82:97], v[150:153], v[114:117], v[82:97]
	ds_read_b128 v[174:177], v221 offset:23072
	v_cvt_pk_bf16_f32 v44, v46, v47
	v_cvt_pk_bf16_f32 v45, v48, v49
	v_exp_f32_e32 v50, v50
	v_exp_f32_e32 v51, v51
	s_waitcnt lgkmcnt(4)
	v_mfma_f32_32x32x16_bf16 v[66:81], v[154:157], v[118:121], v[66:81]
	ds_read_b128 v[180:183], v221 offset:18496
	v_exp_f32_e32 v52, v52
	v_exp_f32_e32 v53, v53
	v_mfma_f32_32x32x16_bf16 v[82:97], v[158:161], v[118:121], v[82:97]
	ds_read_b128 v[184:187], v221 offset:23104
	v_add_f32_e32 v231, v231, v50
	v_add_f32_e32 v232, v232, v51
	v_exp_f32_e32 v54, v54
	v_exp_f32_e32 v55, v55
	s_waitcnt lgkmcnt(4)
	v_mfma_f32_32x32x16_bf16 v[2:17], v[162:165], v[34:37], v[2:17]
	ds_read_b128 v[188:191], v221 offset:18528
	v_add_f32_e32 v231, v231, v52
	v_add_f32_e32 v232, v232, v53
	v_exp_f32_e32 v56, v56
	v_exp_f32_e32 v57, v57
	v_mfma_f32_32x32x16_bf16 v[18:33], v[166:169], v[34:37], v[18:33]
	ds_read_b128 v[192:195], v221 offset:23136
	v_add_f32_e32 v231, v231, v54
	v_add_f32_e32 v232, v232, v55
	v_add_f32_e32 v231, v231, v56
	v_add_f32_e32 v232, v232, v57
	s_waitcnt lgkmcnt(4)
	v_mfma_f32_32x32x16_bf16 v[2:17], v[170:173], v[42:45], v[2:17]
	v_cvt_pk_bf16_f32 v50, v50, v51
	v_cvt_pk_bf16_f32 v51, v52, v53
	v_cvt_pk_bf16_f32 v52, v54, v55
	v_cvt_pk_bf16_f32 v53, v56, v57
	v_exp_f32_e32 v58, v58
	v_mfma_f32_32x32x16_bf16 v[18:33], v[174:177], v[42:45], v[18:33]
	v_exp_f32_e32 v59, v59
	v_exp_f32_e32 v60, v60
	v_exp_f32_e32 v61, v61
	s_waitcnt lgkmcnt(2)
	v_mfma_f32_32x32x16_bf16 v[2:17], v[180:183], v[50:53], v[2:17]
	v_add_f32_e32 v231, v231, v58
	v_add_f32_e32 v232, v232, v59
	v_exp_f32_e32 v62, v62
	v_mfma_f32_32x32x16_bf16 v[18:33], v[184:187], v[50:53], v[18:33]
	v_exp_f32_e32 v63, v63
	v_add_f32_e32 v231, v231, v60
	v_add_f32_e32 v232, v232, v61
	v_exp_f32_e32 v64, v64
	v_exp_f32_e32 v65, v65
	v_add_f32_e32 v231, v231, v62
	v_add_f32_e32 v232, v232, v63
	v_add_f32_e32 v231, v231, v64
	v_add_f32_e32 v232, v232, v65
	v_cvt_pk_bf16_f32 v58, v58, v59
	v_cvt_pk_bf16_f32 v59, v60, v61
	v_cvt_pk_bf16_f32 v60, v62, v63
	v_cvt_pk_bf16_f32 v61, v64, v65
	s_waitcnt lgkmcnt(0)
	s_nop 0
	v_mfma_f32_32x32x16_bf16 v[2:17], v[188:191], v[58:61], v[2:17]
	v_mfma_f32_32x32x16_bf16 v[18:33], v[192:195], v[58:61], v[18:33]
	s_waitcnt lgkmcnt(0)
	s_barrier
	s_mov_b64 s[24:25], s[14:15]
	s_add_i32 s2, s2, s88
	s_cmpk_lt_i32 s2, 0x200
	s_cbranch_scc0 .Lmla_lastpf
	s_lshr_b32 s17, s2, 4
	s_and_b32 s18, s2, 15
	s_mul_i32 s19, s17, 0xcc000
	s_add_u32 s4, s78, s19
	s_addc_u32 s5, s79, 0
	s_mul_i32 s19, s17, 0x88000
	s_add_u32 s19, s19, 0x1a00000
	s_add_u32 s10, s78, s19
	s_addc_u32 s11, s79, 0
	s_lshl_b32 s19, s17, 12
	s_lshl_b32 s20, s18, 8
	s_add_u32 s19, s19, s20
	s_mul_i32 s19, s19, 0xc0
	s_add_u32 s19, s19, 0x1400000
	s_add_u32 s12, s80, s19
	s_addc_u32 s13, s81, 0
	s_lshr_b32 s19, s17, 3
	s_lshl_b32 s19, s19, 12
	s_add_u32 s19, s19, s20
	s_lshl_b32 s19, s19, 10
	s_and_b32 s21, s17, 7
	s_lshl_b32 s21, s21, 7
	s_add_u32 s19, s19, s21
	s_add_u32 s19, s19, 0x7900000
	s_add_u32 s14, s80, s19
	s_addc_u32 s15, s81, 0
	global_load_dwordx4 v[98:101], v237, s[12:13] offset:0
	global_load_dwordx4 v[102:105], v237, s[12:13] offset:32
	global_load_dwordx4 v[106:109], v237, s[12:13] offset:64
	global_load_dwordx4 v[110:113], v237, s[12:13] offset:96
	global_load_dwordx4 v[114:117], v237, s[12:13] offset:128
	global_load_dwordx4 v[118:121], v237, s[12:13] offset:160
	global_load_dwordx4 v[34:37], v226, s[4:5]
	global_load_dwordx4 v[38:41], v227, s[4:5]
	global_load_dwordx4 v[42:45], v228, s[4:5]
	global_load_dwordx4 v[46:49], v229, s[10:11]
	s_add_u32 s4, s4, 0x6000
	s_addc_u32 s5, s5, 0
	global_load_dwordx4 v[50:53], v226, s[4:5]
	global_load_dwordx4 v[54:57], v227, s[4:5]
	global_load_dwordx4 v[58:61], v228, s[4:5]
	global_load_dwordx4 v[62:65], v229, s[10:11] offset:128
	global_load_dwordx4 v[216:219], v229, s[10:11] offset:256
	s_add_u32 s4, s4, 0x6000
	s_addc_u32 s5, s5, 0
	s_add_u32 s10, s10, 0x180
	s_addc_u32 s11, s11, 0
	s_branch .Lmla_nopf
.Lmla_lastpf:
	s_getpc_b64 s[26:27]
	s_mov_b32 m0, 0x22800
	v_lshlrev_b32_e32 v1, 7, v0
	global_load_lds_dword v1, s[26:27]
.Lmla_nopf:
	ds_read_b128 v[162:165], v221 offset:27648
	ds_read_b128 v[166:169], v221 offset:32256
	ds_read_b128 v[170:173], v221 offset:27680
	v_exp_f32_e32 v66, v66
	v_exp_f32_e32 v67, v67
	v_exp_f32_e32 v68, v68
	v_exp_f32_e32 v69, v69
	v_add_f32_e32 v231, v231, v66
	v_add_f32_e32 v232, v232, v67
	v_exp_f32_e32 v70, v70
	v_exp_f32_e32 v71, v71
	v_add_f32_e32 v231, v231, v68
	v_add_f32_e32 v232, v232, v69
	v_exp_f32_e32 v72, v72
	v_exp_f32_e32 v73, v73
	v_add_f32_e32 v231, v231, v70
	v_add_f32_e32 v232, v232, v71
	v_add_f32_e32 v231, v231, v72
	v_add_f32_e32 v232, v232, v73
	v_cvt_pk_bf16_f32 v66, v66, v67
	v_cvt_pk_bf16_f32 v67, v68, v69
	v_cvt_pk_bf16_f32 v68, v70, v71
	v_cvt_pk_bf16_f32 v69, v72, v73
	s_waitcnt lgkmcnt(1)
	s_nop 0
	v_mfma_f32_32x32x16_bf16 v[2:17], v[162:165], v[66:69], v[2:17]
	ds_read_b128 v[174:177], v221 offset:32288
	v_mfma_f32_32x32x16_bf16 v[18:33], v[166:169], v[66:69], v[18:33]
	ds_read_b128 v[180:183], v221 offset:27712
	v_exp_f32_e32 v74, v74
	v_exp_f32_e32 v75, v75
	v_exp_f32_e32 v76, v76
	v_exp_f32_e32 v77, v77
	v_add_f32_e32 v231, v231, v74
	v_add_f32_e32 v232, v232, v75
	v_exp_f32_e32 v78, v78
	v_exp_f32_e32 v79, v79
	v_add_f32_e32 v231, v231, v76
	v_add_f32_e32 v232, v232, v77
	v_exp_f32_e32 v80, v80
	v_exp_f32_e32 v81, v81
	v_add_f32_e32 v231, v231, v78
	v_add_f32_e32 v232, v232, v79
	v_add_f32_e32 v231, v231, v80
	v_add_f32_e32 v232, v232, v81
	v_cvt_pk_bf16_f32 v74, v74, v75
	v_cvt_pk_bf16_f32 v75, v76, v77
	v_cvt_pk_bf16_f32 v76, v78, v79
	v_cvt_pk_bf16_f32 v77, v80, v81
	s_waitcnt lgkmcnt(1)
	s_nop 0
	v_mfma_f32_32x32x16_bf16 v[2:17], v[170:173], v[74:77], v[2:17]
	ds_read_b128 v[184:187], v221 offset:32320
	v_mfma_f32_32x32x16_bf16 v[18:33], v[174:177], v[74:77], v[18:33]
	ds_read_b128 v[188:191], v221 offset:27744
	v_exp_f32_e32 v82, v82
	v_exp_f32_e32 v83, v83
	v_exp_f32_e32 v84, v84
	v_exp_f32_e32 v85, v85
	v_add_f32_e32 v231, v231, v82
	v_add_f32_e32 v232, v232, v83
	v_exp_f32_e32 v86, v86
	v_exp_f32_e32 v87, v87
	v_add_f32_e32 v231, v231, v84
	v_add_f32_e32 v232, v232, v85
	v_exp_f32_e32 v88, v88
	v_exp_f32_e32 v89, v89
	v_add_f32_e32 v231, v231, v86
	v_add_f32_e32 v232, v232, v87
	v_add_f32_e32 v231, v231, v88
	v_add_f32_e32 v232, v232, v89
	v_cvt_pk_bf16_f32 v82, v82, v83
	v_cvt_pk_bf16_f32 v83, v84, v85
	v_cvt_pk_bf16_f32 v84, v86, v87
	v_cvt_pk_bf16_f32 v85, v88, v89
	s_waitcnt lgkmcnt(1)
	s_nop 0
	v_mfma_f32_32x32x16_bf16 v[2:17], v[180:183], v[82:85], v[2:17]
	ds_read_b128 v[192:195], v221 offset:32352
	v_mfma_f32_32x32x16_bf16 v[18:33], v[184:187], v[82:85], v[18:33]
	v_exp_f32_e32 v90, v90
	v_exp_f32_e32 v91, v91
	v_exp_f32_e32 v92, v92
	v_exp_f32_e32 v93, v93
	v_add_f32_e32 v231, v231, v90
	v_add_f32_e32 v232, v232, v91
	v_exp_f32_e32 v94, v94
	v_exp_f32_e32 v95, v95
	v_add_f32_e32 v231, v231, v92
	v_add_f32_e32 v232, v232, v93
	v_exp_f32_e32 v96, v96
	v_exp_f32_e32 v97, v97
	v_add_f32_e32 v231, v231, v94
	v_add_f32_e32 v232, v232, v95
	v_add_f32_e32 v231, v231, v96
	v_add_f32_e32 v232, v232, v97
	v_cvt_pk_bf16_f32 v90, v90, v91
	v_cvt_pk_bf16_f32 v91, v92, v93
	v_cvt_pk_bf16_f32 v92, v94, v95
	v_cvt_pk_bf16_f32 v93, v96, v97
	s_waitcnt lgkmcnt(0)
	s_nop 0
	v_mfma_f32_32x32x16_bf16 v[2:17], v[188:191], v[90:93], v[2:17]
	v_mfma_f32_32x32x16_bf16 v[18:33], v[192:195], v[90:93], v[18:33]
	s_waitcnt lgkmcnt(0)
	s_barrier
	v_add_f32_e32 v231, v231, v232
	v_mov_b32_e32 v235, v231
	s_nop 1
	v_permlane32_swap_b32_e32 v231, v235
	v_add_f32_e32 v234, v231, v235
	v_mov_b32_e32 v233, v234
	v_div_scale_f32 v235, s[22:23], v234, v234, 1.0
	v_rcp_f32_e32 v179, v235
	v_div_scale_f32 v196, vcc, 1.0, v234, 1.0
	v_fma_f32 v197, -v235, v179, 1.0
	v_fmac_f32_e32 v179, v197, v179
	v_mul_f32_e32 v197, v196, v179
	v_fma_f32 v199, -v235, v197, v196
	v_fmac_f32_e32 v197, v199, v179
	v_fma_f32 v235, -v235, v197, v196
	v_div_fmas_f32 v235, v235, v179, v197
	v_div_fixup_f32 v234, v235, v234, 1.0
	s_nop 15
	v_mul_f32_e32 v2, v2, v234
	v_mul_f32_e32 v3, v3, v234
	v_mul_f32_e32 v4, v4, v234
	v_mul_f32_e32 v5, v5, v234
	v_mul_f32_e32 v6, v6, v234
	v_mul_f32_e32 v7, v7, v234
	v_mul_f32_e32 v8, v8, v234
	v_mul_f32_e32 v9, v9, v234
	v_mul_f32_e32 v10, v10, v234
	v_mul_f32_e32 v11, v11, v234
	v_mul_f32_e32 v12, v12, v234
	v_mul_f32_e32 v13, v13, v234
	v_mul_f32_e32 v14, v14, v234
	v_mul_f32_e32 v15, v15, v234
	v_mul_f32_e32 v16, v16, v234
	v_mul_f32_e32 v17, v17, v234
	v_mul_f32_e32 v18, v18, v234
	v_mul_f32_e32 v19, v19, v234
	v_mul_f32_e32 v20, v20, v234
	v_mul_f32_e32 v21, v21, v234
	v_mul_f32_e32 v22, v22, v234
	v_mul_f32_e32 v23, v23, v234
	v_mul_f32_e32 v24, v24, v234
	v_mul_f32_e32 v25, v25, v234
	v_mul_f32_e32 v26, v26, v234
	v_mul_f32_e32 v27, v27, v234
	v_mul_f32_e32 v28, v28, v234
	v_mul_f32_e32 v29, v29, v234
	v_mul_f32_e32 v30, v30, v234
	v_mul_f32_e32 v31, v31, v234
	v_mul_f32_e32 v32, v32, v234
	v_mul_f32_e32 v33, v33, v234
	v_mov_b32_e32 v235, 0
	v_fmac_f32_e32 v235, 0, v2
	v_fmac_f32_e32 v235, 0, v3
	v_fmac_f32_e32 v235, 0, v4
	v_fmac_f32_e32 v235, 0, v5
	v_fmac_f32_e32 v235, 0, v6
	v_fmac_f32_e32 v235, 0, v7
	v_fmac_f32_e32 v235, 0, v8
	v_fmac_f32_e32 v235, 0, v9
	v_fmac_f32_e32 v235, 0, v10
	v_fmac_f32_e32 v235, 0, v11
	v_fmac_f32_e32 v235, 0, v12
	v_fmac_f32_e32 v235, 0, v13
	v_fmac_f32_e32 v235, 0, v14
	v_fmac_f32_e32 v235, 0, v15
	v_fmac_f32_e32 v235, 0, v16
	v_fmac_f32_e32 v235, 0, v17
	v_fmac_f32_e32 v235, 0, v18
	v_fmac_f32_e32 v235, 0, v19
	v_fmac_f32_e32 v235, 0, v20
	v_fmac_f32_e32 v235, 0, v21
	v_fmac_f32_e32 v235, 0, v22
	v_fmac_f32_e32 v235, 0, v23
	v_fmac_f32_e32 v235, 0, v24
	v_fmac_f32_e32 v235, 0, v25
	v_fmac_f32_e32 v235, 0, v26
	v_fmac_f32_e32 v235, 0, v27
	v_fmac_f32_e32 v235, 0, v28
	v_fmac_f32_e32 v235, 0, v29
	v_fmac_f32_e32 v235, 0, v30
	v_fmac_f32_e32 v235, 0, v31
	v_fmac_f32_e32 v235, 0, v32
	v_fmac_f32_e32 v235, 0, v33
	v_fmac_f32_e32 v235, 0, v233
	v_cmp_u_f32_e32 vcc, v235, v235
	s_cmp_lg_u64 vcc, 0
	s_cselect_b32 s26, 1, 0
	v_mov_b32_e32 v179, 0x186a0
	v_mov_b32_e32 v196, s26
	ds_or_b32 v179, v196
	s_waitcnt lgkmcnt(0)
	s_barrier
	ds_read_b32 v196, v179
	s_waitcnt lgkmcnt(0)
	v_readfirstlane_b32 s26, v196
	s_barrier
	v_mov_b32_e32 v196, 0
	ds_write_b32 v179, v196
	s_cmp_lg_u32 s26, 0
	s_cbranch_scc1 .Lmla_redo
	s_cmpk_lt_i32 s2, 0x200
	s_cbranch_scc1 .Lmla_zw15
	s_waitcnt vmcnt(1)
	s_branch .Lmla_zw
